# e11 plus phase-1 RMS-norm pass: gamma/scale/shift kept in registers per batch index (reload only on change), per-row vmcnt drains removed, counted wait for the next-row prefetch
# baseline (speedup 1.0000x reference)
.LBB0_701:
	s_andn2_b64 vcc, exec, s[2:3]
	s_cbranch_vccnz .LBB0_708
	s_cmpk_gt_i32 s96, 0x7fff
	v_mbcnt_lo_u32_b32 v0, -1, 0
	v_mbcnt_hi_u32_b32 v0, -1, v0
	s_cbranch_scc1 .LBB0_708
	s_ashr_i32 s97, s96, 31
	s_lshl_b64 s[0:1], s[96:97], 12
	s_waitcnt vmcnt(0)
	v_and_b32_e32 v14, 63, v0
	s_waitcnt lgkmcnt(0)
	s_add_u32 s0, s68, s0
	s_addc_u32 s1, s69, s1
	v_lshlrev_b32_e32 v0, 4, v14
	global_load_dwordx4 v[30:33], v0, s[0:1]
	global_load_dwordx4 v[10:13], v0, s[0:1] offset:1024
	global_load_dwordx4 v[6:9], v0, s[0:1] offset:2048
	global_load_dwordx4 v[2:5], v0, s[0:1] offset:3072
	v_readlane_b32 s0, v255, 21
	v_readlane_b32 s1, v255, 22
	v_lshl_add_u64 v[34:35], s[68:69], 0, v[0:1]
	v_lshl_add_u64 v[36:37], s[22:23], 0, v[0:1]
	v_lshl_add_u64 v[38:39], s[0:1], 0, v[0:1]
	v_readlane_b32 s0, v255, 23
	v_readlane_b32 s1, v255, 24
	s_mov_b32 s6, s96
	s_nop 0
	v_lshl_add_u64 v[40:41], s[0:1], 0, v[0:1]
	s_lshl_b64 s[0:1], s[96:97], 11
	s_add_u32 s0, s48, s0
	v_lshlrev_b32_e32 v0, 3, v14
	s_addc_u32 s1, s49, s1
	s_ashr_i32 s55, s54, 31
	v_lshl_add_u64 v[42:43], s[0:1], 0, v[0:1]
	s_lshl_b64 s[0:1], s[54:55], 11
	s_mov_b32 s100, -1
	s_waitcnt vmcnt(0)
	s_branch .LBB0_705
.LBB0_704:
	s_ashr_i32 s3, s6, 13
	s_cmp_eq_u32 s3, s100
	s_cbranch_scc1 .Lmy_nm_noreload
	v_mad_i64_i32 v[56:57], s[6:7], s3, v252, v[40:41]
	v_mad_i64_i32 v[58:59], s[6:7], s3, v252, v[38:39]
	global_load_dwordx4 v[116:119], v[36:37], off
	global_load_dwordx4 v[120:123], v[56:57], off
	global_load_dwordx4 v[124:127], v[58:59], off
	global_load_dwordx4 v[80:83], v[36:37], off offset:1024
	global_load_dwordx4 v[84:87], v[56:57], off offset:1024
	global_load_dwordx4 v[88:91], v[58:59], off offset:1024
	global_load_dwordx4 v[92:95], v[36:37], off offset:2048
	global_load_dwordx4 v[96:99], v[56:57], off offset:2048
	global_load_dwordx4 v[100:103], v[58:59], off offset:2048
	global_load_dwordx4 v[104:107], v[36:37], off offset:3072
	global_load_dwordx4 v[108:111], v[56:57], off offset:3072
	global_load_dwordx4 v[112:115], v[58:59], off offset:3072
	s_mov_b32 s100, s3
	s_waitcnt vmcnt(0)
.Lmy_nm_noreload:
	v_mul_f32_e32 v0, v31, v31
	v_mul_f32_e32 v60, v33, v33
	v_mul_f32_e32 v61, v11, v11
	v_mul_f32_e32 v62, v13, v13
	v_mul_f32_e32 v63, v7, v7
	v_mul_f32_e32 v64, v9, v9
	v_fmac_f32_e32 v0, v30, v30
	v_fmac_f32_e32 v60, v32, v32
	v_fmac_f32_e32 v61, v10, v10
	v_fmac_f32_e32 v62, v12, v12
	v_mul_f32_e32 v65, v3, v3
	v_mul_f32_e32 v66, v5, v5
	v_fmac_f32_e32 v63, v6, v6
	v_fmac_f32_e32 v64, v8, v8
	v_add_f32_e32 v0, v0, v60
	v_add_f32_e32 v60, v61, v62
	v_fmac_f32_e32 v65, v2, v2
	v_fmac_f32_e32 v66, v4, v4
	v_add_f32_e32 v61, v63, v64
	v_add_f32_e32 v0, v0, v60
	v_add_f32_e32 v62, v65, v66
	v_add_f32_e32 v0, v61, v0
	v_add_f32_e32 v0, v62, v0
	ds_swizzle_b32 v60, v0 offset:swizzle(SWAP,1)
	s_and_b64 vcc, exec, s[4:5]
	s_mov_b32 s6, s2
	s_waitcnt lgkmcnt(0)
	v_add_f32_e32 v0, v0, v60
	ds_swizzle_b32 v60, v0 offset:swizzle(SWAP,2)
	s_waitcnt lgkmcnt(0)
	v_add_f32_e32 v0, v0, v60
	ds_swizzle_b32 v60, v0 offset:swizzle(SWAP,4)
	s_waitcnt lgkmcnt(0)
	v_add_f32_e32 v0, v0, v60
	ds_swizzle_b32 v60, v0 offset:swizzle(SWAP,8)
	s_waitcnt lgkmcnt(0)
	v_add_f32_e32 v0, v0, v60
	ds_swizzle_b32 v60, v0 offset:swizzle(SWAP,16)
	s_waitcnt lgkmcnt(0)
	v_add_f32_e32 v0, v0, v60
	v_mov_b32_e32 v60, v0
	s_nop 1
	v_permlane32_swap_b32_e32 v0, v60
	v_add_f32_e32 v0, v0, v60
	v_fmamk_f32 v0, v0, 0x3a800000, v244
	v_rsq_f32_e32 v0, v0
	s_nop 0
	v_pk_mul_f32 v[32:33], v[32:33], v[0:1] op_sel_hi:[1,0]
	v_pk_mul_f32 v[30:31], v[30:31], v[0:1] op_sel_hi:[1,0]
	v_pk_mul_f32 v[12:13], v[12:13], v[0:1] op_sel_hi:[1,0]
	v_pk_mul_f32 v[10:11], v[10:11], v[0:1] op_sel_hi:[1,0]
	v_pk_mul_f32 v[8:9], v[8:9], v[0:1] op_sel_hi:[1,0]
	v_pk_mul_f32 v[6:7], v[6:7], v[0:1] op_sel_hi:[1,0]
	v_mov_b64_e32 v[44:45], v[116:117]
	v_mov_b64_e32 v[46:47], v[118:119]
	v_pk_mul_f32 v[30:31], v[44:45], v[30:31]
	v_pk_mul_f32 v[32:33], v[46:47], v[32:33]
	v_mov_b64_e32 v[48:49], v[120:121]
	v_mov_b64_e32 v[50:51], v[122:123]
	v_pk_add_f32 v[46:47], v[48:49], 1.0 op_sel_hi:[1,0]
	v_pk_add_f32 v[44:45], v[50:51], 1.0 op_sel_hi:[1,0]
	v_mov_b64_e32 v[52:53], v[124:125]
	v_mov_b64_e32 v[54:55], v[126:127]
	v_pk_fma_f32 v[30:31], v[46:47], v[30:31], v[52:53]
	v_pk_fma_f32 v[32:33], v[44:45], v[32:33], v[54:55]
	v_cvt_pk_bf16_f32 v30, v30, v31
	s_nop 0
	v_cvt_pk_bf16_f32 v31, v32, v33
	global_store_dwordx2 v[42:43], v[30:31], off
	v_mov_b64_e32 v[30:31], v[80:81]
	v_mov_b64_e32 v[32:33], v[82:83]
	v_mov_b64_e32 v[44:45], v[84:85]
	v_mov_b64_e32 v[46:47], v[86:87]
	v_mov_b64_e32 v[48:49], v[88:89]
	v_mov_b64_e32 v[50:51], v[90:91]
	v_pk_mul_f32 v[10:11], v[30:31], v[10:11]
	v_pk_mul_f32 v[12:13], v[32:33], v[12:13]
	v_pk_add_f32 v[32:33], v[44:45], 1.0 op_sel_hi:[1,0]
	v_pk_add_f32 v[30:31], v[46:47], 1.0 op_sel_hi:[1,0]
	v_pk_fma_f32 v[10:11], v[32:33], v[10:11], v[48:49]
	v_pk_fma_f32 v[12:13], v[30:31], v[12:13], v[50:51]
	v_cvt_pk_bf16_f32 v10, v10, v11
	s_nop 0
	v_cvt_pk_bf16_f32 v11, v12, v13
	global_store_dwordx2 v[42:43], v[10:11], off offset:512
	s_waitcnt vmcnt(2)
	v_mov_b64_e32 v[10:11], v[92:93]
	v_mov_b64_e32 v[12:13], v[94:95]
	v_mov_b64_e32 v[30:31], v[96:97]
	v_mov_b64_e32 v[32:33], v[98:99]
	v_mov_b64_e32 v[44:45], v[100:101]
	v_mov_b64_e32 v[46:47], v[102:103]
	v_pk_mul_f32 v[6:7], v[6:7], v[10:11]
	v_pk_mul_f32 v[8:9], v[8:9], v[12:13]
	v_pk_add_f32 v[12:13], v[30:31], 1.0 op_sel_hi:[1,0]
	v_pk_add_f32 v[10:11], v[32:33], 1.0 op_sel_hi:[1,0]
	v_pk_fma_f32 v[6:7], v[6:7], v[12:13], v[44:45]
	v_pk_fma_f32 v[8:9], v[8:9], v[10:11], v[46:47]
	v_cvt_pk_bf16_f32 v6, v6, v7
	v_mov_b32_e32 v30, v14
	v_cvt_pk_bf16_f32 v7, v8, v9
	global_store_dwordx2 v[42:43], v[6:7], off offset:1024
	v_mov_b64_e32 v[44:45], v[104:105]
	v_mov_b64_e32 v[46:47], v[106:107]
	v_mov_b64_e32 v[48:49], v[108:109]
	v_mov_b64_e32 v[50:51], v[110:111]
	v_mov_b64_e32 v[52:53], v[112:113]
	v_mov_b64_e32 v[54:55], v[114:115]
	v_pk_mul_f32 v[58:59], v[2:3], v[0:1] op_sel_hi:[1,0]
	v_pk_mul_f32 v[56:57], v[4:5], v[0:1] op_sel_hi:[1,0]
	v_mov_b32_e32 v31, v15
	v_mov_b32_e32 v12, v20
	v_mov_b32_e32 v13, v21
	v_mov_b32_e32 v32, v16
	v_mov_b32_e32 v33, v17
	v_mov_b32_e32 v10, v18
	v_mov_b32_e32 v11, v19
	v_mov_b32_e32 v6, v22
	v_mov_b32_e32 v7, v23
	v_mov_b32_e32 v8, v24
	v_mov_b32_e32 v9, v25
	v_mov_b32_e32 v2, v26
	v_mov_b32_e32 v3, v27
	v_mov_b32_e32 v4, v28
	v_mov_b32_e32 v5, v29
	v_pk_mul_f32 v[14:15], v[58:59], v[44:45]
	v_pk_add_f32 v[20:21], v[48:49], 1.0 op_sel_hi:[1,0]
	v_pk_mul_f32 v[16:17], v[56:57], v[46:47]
	v_pk_add_f32 v[18:19], v[50:51], 1.0 op_sel_hi:[1,0]
	v_pk_fma_f32 v[14:15], v[14:15], v[20:21], v[52:53]
	v_pk_fma_f32 v[16:17], v[16:17], v[18:19], v[54:55]
	v_cvt_pk_bf16_f32 v14, v14, v15
	s_nop 0
	v_cvt_pk_bf16_f32 v15, v16, v17
	global_store_dwordx2 v[42:43], v[14:15], off offset:1536
	v_lshl_add_u64 v[42:43], v[42:43], 0, s[0:1]
	s_cbranch_vccnz .LBB0_707
.LBB0_705:
	s_add_i32 s2, s6, s54
	s_cmpk_gt_i32 s2, 0x7fff
	s_cselect_b64 s[4:5], -1, 0
	s_and_b64 vcc, exec, s[4:5]
	v_mov_b32_e32 v14, v30
	v_mov_b32_e32 v15, v31
	v_mov_b32_e32 v16, v32
	v_mov_b32_e32 v17, v33
	v_mov_b32_e32 v18, v10
	v_mov_b32_e32 v19, v11
	v_mov_b32_e32 v20, v12
	v_mov_b32_e32 v21, v13
	v_mov_b32_e32 v22, v6
	v_mov_b32_e32 v23, v7
	v_mov_b32_e32 v24, v8
	v_mov_b32_e32 v25, v9
	v_mov_b32_e32 v26, v2
	v_mov_b32_e32 v27, v3
	v_mov_b32_e32 v28, v4
	v_mov_b32_e32 v29, v5
	s_cbranch_vccnz .LBB0_704
	s_ashr_i32 s3, s2, 31
	s_lshl_b64 s[8:9], s[2:3], 12
	v_lshl_add_u64 v[26:27], v[34:35], 0, s[8:9]
	global_load_dwordx4 v[14:17], v[26:27], off
	global_load_dwordx4 v[18:21], v[26:27], off offset:1024
	global_load_dwordx4 v[22:25], v[26:27], off offset:2048
	s_nop 0
	global_load_dwordx4 v[26:29], v[26:27], off offset:3072
	s_branch .LBB0_704
